# de-serialised the memory-token rmsnorm row loop (2 instances): the 8 loop-invariant gain loads, each followed by vmcnt(0) that also waited for the previous store, are loaded once before the loop
# baseline (speedup 1.0000x reference)
; __device__ __forceinline__ void rms_row_bf16(const Ctx& c, const float* xrow, const float* gain, bf16* orow, float* copy) {
;     const f32x4* xr = (const f32x4*)xrow + c.lane; f32x4 v[8]; float s = 0.f;
; #pragma unroll
;     for (int j = 0; j < 8; ++j) { v[j] = xr[64 * j]; s += (v[j].x * v[j].x + v[j].y * v[j].y) + (v[j].z * v[j].z + v[j].w * v[j].w); }
;     const float rs = rsqrtf(wave_sum(s) * (1.f / DM) + EPS);
; template <int L>
; __device__ __forceinline__ void layer_body(const Ctx& c, const Args& args, const XcdBarrier& bar, int lo, int hi) {
;     ...
;             for (int r = (c.gw + c.NGW - 1024) % c.NGW; r < 1024; r += c.NGW) rms_row_bf16(c, mem + (size_t)r * DM, norm_mem + L * DM, MEMN + (size_t)r * DM, nullptr);
.LBB0_1588:
	s_add_i32 s2, s9, 0xfffffc00
	s_sub_i32 s6, 0x400, s9
	s_ashr_i32 s3, s2, 31
	s_max_i32 s2, s2, s6
	s_mul_hi_u32 s6, s2, s10
	s_mul_i32 s6, s6, s8
	s_sub_i32 s2, s2, s6
	s_sub_i32 s6, s2, s8
	s_cmp_ge_u32 s2, s8
	s_cselect_b32 s2, s6, s2
	s_sub_i32 s6, s2, s8
	s_cmp_ge_u32 s2, s8
	s_cselect_b32 s2, s6, s2
	s_xor_b32 s2, s2, s3
	s_sub_i32 s2, s2, s3
	s_cmpk_gt_i32 s2, 0x3ff
	s_cbranch_scc1 .LBB0_1591
	v_mbcnt_lo_u32_b32 v3, -1, 0
	v_mbcnt_hi_u32_b32 v4, -1, v3
	v_and_b32_e32 v3, 64, v4
	v_add_u32_e32 v5, 64, v3
	v_xor_b32_e32 v3, 1, v4
	v_cmp_lt_i32_e32 vcc, v3, v5
	v_xor_b32_e32 v6, 2, v4
	v_readlane_b32 s8, v253, 15
	v_cndmask_b32_e32 v3, v4, v3, vcc
	v_cmp_lt_i32_e32 vcc, v6, v5
	v_readlane_b32 s16, v253, 23
	v_readlane_b32 s17, v253, 24
	v_cndmask_b32_e32 v6, v4, v6, vcc
	v_lshlrev_b32_e32 v51, 2, v6
	v_xor_b32_e32 v6, 4, v4
	v_cmp_lt_i32_e32 vcc, v6, v5
	s_mov_b64 s[6:7], 0x2000
	s_ashr_i32 s3, s2, 31
	v_cndmask_b32_e32 v6, v4, v6, vcc
	v_lshlrev_b32_e32 v54, 2, v6
	v_xor_b32_e32 v6, 8, v4
	v_cmp_lt_i32_e32 vcc, v6, v5
	v_readlane_b32 s10, v253, 17
	v_readlane_b32 s11, v253, 18
	v_cndmask_b32_e32 v6, v4, v6, vcc
	v_lshlrev_b32_e32 v55, 2, v6
	v_xor_b32_e32 v6, 16, v4
	v_cmp_lt_i32_e32 vcc, v6, v5
	v_readlane_b32 s9, v253, 16
	v_lshlrev_b32_e32 v3, 2, v3
	v_cndmask_b32_e32 v6, v4, v6, vcc
	v_lshlrev_b32_e32 v56, 2, v6
	v_xor_b32_e32 v6, 32, v4
	v_cmp_lt_i32_e32 vcc, v6, v5
	v_mov_b32_e32 v5, 0
	v_mov_b32_e32 v58, 0x358637bd
	v_cndmask_b32_e32 v4, v4, v6, vcc
	v_lshlrev_b32_e32 v57, 2, v4
	v_lshlrev_b32_e32 v4, 4, v164
	v_lshl_add_u64 v[6:7], s[16:17], 0, v[4:5]
	v_lshl_add_u64 v[36:37], v[6:7], 0, s[6:7]
	s_mov_b64 s[6:7], 0x3000
	v_lshl_add_u64 v[38:39], v[6:7], 0, s[6:7]
	s_mov_b64 s[6:7], 0x3400
	v_lshl_add_u64 v[40:41], v[6:7], 0, s[6:7]
	s_mov_b64 s[6:7], 0x3800
	v_lshl_add_u64 v[42:43], v[6:7], 0, s[6:7]
	s_mov_b64 s[6:7], 0x3c00
	v_lshl_add_u64 v[44:45], v[6:7], 0, s[6:7]
	s_lshl_b64 s[6:7], s[2:3], 13
	s_add_u32 s6, s10, s6
	s_addc_u32 s7, s11, s7
	v_lshl_add_u64 v[6:7], s[6:7], 0, v[4:5]
	s_mov_b64 s[6:7], 0x1000
	s_ashr_i32 s87, s86, 31
	s_waitcnt lgkmcnt(0)
	v_lshl_add_u64 v[46:47], v[6:7], 0, s[6:7]
	s_lshl_b64 s[6:7], s[86:87], 13
	s_lshl_b64 s[8:9], s[2:3], 12
	v_readlane_b32 s10, v253, 0
	v_readlane_b32 s11, v253, 1
	s_add_u32 s8, s10, s8
	v_lshlrev_b32_e32 v4, 3, v164
	s_addc_u32 s9, s11, s9
	v_lshl_add_u64 v[4:5], s[8:9], 0, v[4:5]
	s_mov_b64 s[8:9], 0x31600000
	v_lshl_add_u64 v[48:49], v[4:5], 0, s[8:9]
	s_lshl_b64 s[8:9], s[86:87], 12
	s_movk_i32 s3, 0x7fff
	v_mov_b32_e32 v59, 1
	s_mov_b32 s10, 0x800000
	v_readlane_b32 s12, v253, 19
	v_readlane_b32 s13, v253, 20
	v_readlane_b32 s14, v253, 21
	v_readlane_b32 s15, v253, 22
	v_readlane_b32 s18, v253, 25
	v_readlane_b32 s19, v253, 26
	v_readlane_b32 s20, v253, 27
	v_readlane_b32 s21, v253, 28
	v_readlane_b32 s22, v253, 29
	v_readlane_b32 s23, v253, 30
	global_load_dwordx4 v[68:71], v[36:37], off
	global_load_dwordx4 v[80:83], v[36:37], off offset:1024
	global_load_dwordx4 v[124:127], v[36:37], off offset:2048
	global_load_dwordx4 v[128:131], v[36:37], off offset:3072
	global_load_dwordx4 v[132:135], v[38:39], off
	global_load_dwordx4 v[136:139], v[40:41], off
	global_load_dwordx4 v[140:143], v[42:43], off
	global_load_dwordx4 v[144:147], v[44:45], off
	s_waitcnt vmcnt(0)
.LBB0_1590:
	global_load_dwordx4 v[32:35], v[46:47], off offset:-4096
	global_load_dwordx4 v[28:31], v[46:47], off offset:-3072
	global_load_dwordx4 v[24:27], v[46:47], off offset:-2048
	global_load_dwordx4 v[20:23], v[46:47], off offset:-1024
	global_load_dwordx4 v[12:15], v[46:47], off
	global_load_dwordx4 v[16:19], v[46:47], off offset:1024
	s_add_i32 s2, s2, s86
	s_cmpk_lt_i32 s2, 0x400
	s_waitcnt vmcnt(0)
	v_mov_b32_e32 v6, v33
	v_mov_b32_e32 v7, v29
	v_mov_b32_e32 v4, v32
	v_mov_b32_e32 v5, v28
	v_pk_mul_f32 v[6:7], v[6:7], v[6:7]
	v_mov_b32_e32 v8, v35
	v_mov_b32_e32 v9, v31
	v_pk_fma_f32 v[4:5], v[4:5], v[4:5], v[6:7]
	v_mov_b32_e32 v6, v34
	v_mov_b32_e32 v7, v30
	v_pk_mul_f32 v[8:9], v[8:9], v[8:9]
	s_nop 0
	v_pk_fma_f32 v[6:7], v[6:7], v[6:7], v[8:9]
	v_pk_mul_f32 v[8:9], v[24:25], v[24:25]
	v_pk_add_f32 v[4:5], v[4:5], v[6:7]
	v_pk_mul_f32 v[6:7], v[26:27], v[26:27]
	v_pk_add_f32 v[4:5], v[4:5], v[4:5] op_sel:[0,1] op_sel_hi:[1,0]
	v_pk_mov_b32 v[10:11], v[8:9], v[6:7] op_sel:[1,0]
	v_mov_b32_e32 v9, v7
	v_pk_add_f32 v[6:7], v[10:11], v[8:9]
	v_mul_f32_e32 v8, v12, v12
	v_mul_f32_e32 v9, v13, v13
	v_pk_add_f32 v[6:7], v[6:7], v[6:7] op_sel:[0,1] op_sel_hi:[1,0]
	v_mov_b32_e32 v5, v8
	v_mov_b32_e32 v7, v9
	v_pk_add_f32 v[4:5], v[4:5], v[6:7]
	v_mul_f32_e32 v6, v21, v21
	v_mul_f32_e32 v8, v23, v23
	v_mul_f32_e32 v10, v14, v14
	v_mul_f32_e32 v11, v15, v15
	v_pk_fma_f32 v[6:7], v[20:21], v[20:21], v[6:7] op_sel_hi:[1,1,0]
	v_pk_fma_f32 v[8:9], v[22:23], v[22:23], v[8:9] op_sel_hi:[1,1,0]
	v_mov_b32_e32 v7, v10
	v_mov_b32_e32 v9, v11
	v_pk_add_f32 v[6:7], v[6:7], v[8:9]
	s_nop 0
	v_pk_add_f32 v[52:53], v[4:5], v[6:7]
	v_pk_mul_f32 v[4:5], v[18:19], v[18:19]
	v_pk_mul_f32 v[6:7], v[16:17], v[16:17]
	v_pk_add_f32 v[52:53], v[52:53], v[52:53] op_sel:[0,1] op_sel_hi:[1,0]
	v_pk_mov_b32 v[8:9], v[6:7], v[4:5] op_sel:[1,0]
	v_mov_b32_e32 v7, v5
	v_pk_add_f32 v[60:61], v[8:9], v[6:7]
	global_load_dwordx4 v[8:11], v[46:47], off offset:2048
	global_load_dwordx4 v[4:7], v[46:47], off offset:3072
	v_pk_add_f32 v[60:61], v[60:61], v[60:61] op_sel:[0,1] op_sel_hi:[1,0]
	v_lshl_add_u64 v[46:47], v[46:47], 0, s[6:7]
	s_waitcnt vmcnt(0)
; __device__ __forceinline__ void rms_row_bf16(const Ctx& c, const float* xrow, const float* gain, bf16* orow, float* copy) {
;     ...
;     for (int j = 0; j < 8; ++j) { v[j] = xr[64 * j]; s += (v[j].x * v[j].x + v[j].y * v[j].y) + (v[j].z * v[j].z + v[j].w * v[j].w); }
;     const float rs = rsqrtf(wave_sum(s) * (1.f / DM) + EPS);
	v_mul_f32_e32 v50, v4, v4
	v_mul_f32_e32 v62, v5, v5
	v_mov_b32_e32 v53, v50
	v_mov_b32_e32 v61, v62
	v_mul_f32_e32 v50, v9, v9
	v_mul_f32_e32 v63, v6, v6
	v_pk_add_f32 v[52:53], v[52:53], v[60:61]
	v_pk_fma_f32 v[60:61], v[8:9], v[8:9], v[50:51] op_sel_hi:[1,1,0]
	v_mul_f32_e32 v50, v11, v11
	v_mul_f32_e32 v64, v7, v7
	v_mov_b32_e32 v61, v63
	v_pk_fma_f32 v[62:63], v[10:11], v[10:11], v[50:51] op_sel_hi:[1,1,0]
	s_nop 0
	v_mov_b32_e32 v63, v64
	v_pk_add_f32 v[60:61], v[60:61], v[62:63]
	s_nop 0
	v_pk_add_f32 v[52:53], v[52:53], v[60:61]
	v_mov_b32_e32 v60, v68
	v_mov_b32_e32 v61, v69
	v_mov_b32_e32 v62, v70
	v_mov_b32_e32 v63, v71
	v_add_f32_e32 v50, v52, v53
	v_mov_b32_e32 v53, v34
	v_mov_b32_e32 v34, v33
	s_waitcnt lgkmcnt(0)
	s_nop 1
	v_add_f32_dpp v50, v50, v50 quad_perm:[1,0,3,2] row_mask:0xf bank_mask:0xf
	s_waitcnt lgkmcnt(0)
	s_nop 1
	v_add_f32_dpp v50, v50, v50 quad_perm:[2,3,0,1] row_mask:0xf bank_mask:0xf
	s_waitcnt lgkmcnt(0)
	s_nop 1
	v_add_f32_dpp v50, v50, v50 row_half_mirror row_mask:0xf bank_mask:0xf
	s_waitcnt lgkmcnt(0)
	s_nop 1
	v_add_f32_dpp v50, v50, v50 row_mirror row_mask:0xf bank_mask:0xf
	s_waitcnt lgkmcnt(0)
	v_mov_b32_e32 v52, v50
	s_nop 1
	v_permlane16_swap_b32_e32 v50, v52
	v_add_f32_e32 v50, v50, v52
	s_waitcnt lgkmcnt(0)
; __device__ __forceinline__ unsigned pk2(float lo, float hi) { return f2bf(lo) | (f2bf(hi) << 16); }
; __device__ __forceinline__ void rms_row_bf16(const Ctx& c, const float* xrow, const float* gain, bf16* orow, float* copy) {
;     ...
;     const float rs = rsqrtf(wave_sum(s) * (1.f / DM) + EPS);
;     if (copy) {
; #pragma unroll
;         for (int j = 0; j < 8; ++j) ((f32x4*)copy + c.lane)[64 * j] = v[j]; }
;     const f32x4* gr = (const f32x4*)gain + c.lane; v2u* o8 = (v2u*)orow + c.lane;
; #pragma unroll
;     for (int j = 0; j < 8; ++j) { const f32x4 g = gr[64 * j]; v2u o; o.x = pk2(v[j].x * rs * g.x, v[j].y * rs * g.y); o.y = pk2(v[j].z * rs * g.z, v[j].w * rs * g.w); o8[64 * j] = o; }
	v_mov_b32_e32 v52, v50
	s_nop 1
	v_permlane32_swap_b32_e32 v50, v52
	v_add_f32_e32 v50, v50, v52
	v_fmamk_f32 v50, v50, 0x3a000000, v58
	v_cmp_gt_f32_e32 vcc, s10, v50
	v_mul_f32_e32 v52, 0x4b800000, v50
	v_mov_b32_e32 v64, v60
	v_cndmask_b32_e32 v50, v50, v52, vcc
	v_rsq_f32_e32 v50, v50
	v_mov_b32_e32 v65, v62
	v_mov_b32_e32 v62, v61
	v_mul_f32_e32 v52, 0x45800000, v50
	v_cndmask_b32_e32 v50, v50, v52, vcc
	v_mov_b32_e32 v52, v32
	v_pk_mul_f32 v[52:53], v[52:53], v[50:51] op_sel_hi:[1,0]
	v_pk_mul_f32 v[32:33], v[34:35], v[50:51] op_sel_hi:[1,0]
	v_pk_mul_f32 v[52:53], v[64:65], v[52:53]
	v_pk_mul_f32 v[32:33], v[62:63], v[32:33]
	v_and_b32_sdwa v34, v53, v59 dst_sel:DWORD dst_unused:UNUSED_PAD src0_sel:WORD_1 src1_sel:DWORD
	v_and_b32_sdwa v35, v52, v59 dst_sel:DWORD dst_unused:UNUSED_PAD src0_sel:WORD_1 src1_sel:DWORD
	v_add3_u32 v35, v52, v35, s3
	v_add3_u32 v34, v53, v34, s3
	v_and_b32_sdwa v52, v33, v59 dst_sel:DWORD dst_unused:UNUSED_PAD src0_sel:WORD_1 src1_sel:DWORD
	v_and_b32_sdwa v53, v32, v59 dst_sel:DWORD dst_unused:UNUSED_PAD src0_sel:WORD_1 src1_sel:DWORD
	v_add3_u32 v33, v33, v52, s3
	v_add3_u32 v32, v32, v53, s3
	v_and_b32_e32 v33, 0xffff0000, v33
	v_and_b32_e32 v32, 0xffff0000, v32
	v_or_b32_sdwa v33, v33, v34 dst_sel:DWORD dst_unused:UNUSED_PAD src0_sel:DWORD src1_sel:WORD_1
	v_or_b32_sdwa v32, v32, v35 dst_sel:DWORD dst_unused:UNUSED_PAD src0_sel:DWORD src1_sel:WORD_1
	global_store_dwordx2 v[48:49], v[32:33], off
	v_mov_b32_e32 v32, v80
	v_mov_b32_e32 v33, v81
	v_mov_b32_e32 v34, v82
	v_mov_b32_e32 v35, v83
	v_mov_b32_e32 v53, v30
	v_mov_b32_e32 v30, v29
	v_mov_b32_e32 v52, v28
	v_pk_mul_f32 v[28:29], v[30:31], v[50:51] op_sel_hi:[1,0]
	v_pk_mul_f32 v[52:53], v[52:53], v[50:51] op_sel_hi:[1,0]
	v_mov_b32_e32 v61, v34
	v_mov_b32_e32 v34, v33
	v_mov_b32_e32 v60, v32
	v_pk_mul_f32 v[28:29], v[34:35], v[28:29]
	v_pk_mul_f32 v[52:53], v[60:61], v[52:53]
	s_nop 7
	s_nop 1
	v_cvt_pk_bf16_f32 v29, v53, v29
	v_cvt_pk_bf16_f32 v28, v52, v28
	global_store_dwordx2 v[48:49], v[28:29], off offset:512
	v_mov_b32_e32 v28, v124
	v_mov_b32_e32 v29, v125
	v_mov_b32_e32 v30, v126
	v_mov_b32_e32 v31, v127
	v_mov_b32_e32 v33, v26
	v_mov_b32_e32 v26, v25
	v_mov_b32_e32 v32, v24
	v_pk_mul_f32 v[24:25], v[26:27], v[50:51] op_sel_hi:[1,0]
	v_pk_mul_f32 v[32:33], v[32:33], v[50:51] op_sel_hi:[1,0]
	v_mov_b32_e32 v35, v30
	v_mov_b32_e32 v30, v29
	v_mov_b32_e32 v34, v28
	v_pk_mul_f32 v[24:25], v[30:31], v[24:25]
	v_pk_mul_f32 v[32:33], v[34:35], v[32:33]
	s_nop 7
	s_nop 1
	v_cvt_pk_bf16_f32 v25, v33, v25
	v_cvt_pk_bf16_f32 v24, v32, v24
	global_store_dwordx2 v[48:49], v[24:25], off offset:1024
	v_mov_b32_e32 v24, v128
	v_mov_b32_e32 v25, v129
	v_mov_b32_e32 v26, v130
	v_mov_b32_e32 v27, v131
	v_mov_b32_e32 v29, v22
	v_mov_b32_e32 v22, v21
	v_mov_b32_e32 v28, v20
	v_pk_mul_f32 v[20:21], v[22:23], v[50:51] op_sel_hi:[1,0]
	v_pk_mul_f32 v[28:29], v[28:29], v[50:51] op_sel_hi:[1,0]
	v_mov_b32_e32 v31, v26
	v_mov_b32_e32 v26, v25
	v_mov_b32_e32 v30, v24
	v_pk_mul_f32 v[20:21], v[26:27], v[20:21]
	v_pk_mul_f32 v[28:29], v[30:31], v[28:29]
	s_nop 7
	s_nop 1
	v_cvt_pk_bf16_f32 v21, v29, v21
	v_cvt_pk_bf16_f32 v20, v28, v20
	global_store_dwordx2 v[48:49], v[20:21], off offset:1536
	v_mov_b32_e32 v20, v132
	v_mov_b32_e32 v21, v133
	v_mov_b32_e32 v22, v134
	v_mov_b32_e32 v23, v135
	v_mov_b32_e32 v25, v14
	v_mov_b32_e32 v14, v13
	v_mov_b32_e32 v24, v12
	v_pk_mul_f32 v[12:13], v[14:15], v[50:51] op_sel_hi:[1,0]
	v_pk_mul_f32 v[24:25], v[24:25], v[50:51] op_sel_hi:[1,0]
	v_mov_b32_e32 v27, v22
	v_mov_b32_e32 v22, v21
	v_mov_b32_e32 v26, v20
	v_pk_mul_f32 v[12:13], v[22:23], v[12:13]
	v_pk_mul_f32 v[24:25], v[26:27], v[24:25]
	s_nop 7
	s_nop 1
	v_cvt_pk_bf16_f32 v13, v25, v13
	v_cvt_pk_bf16_f32 v12, v24, v12
	global_store_dwordx2 v[48:49], v[12:13], off offset:2048
	v_mov_b32_e32 v12, v136
	v_mov_b32_e32 v13, v137
	v_mov_b32_e32 v14, v138
	v_mov_b32_e32 v15, v139
	v_mov_b32_e32 v21, v18
	v_mov_b32_e32 v18, v17
	v_mov_b32_e32 v20, v16
	v_pk_mul_f32 v[16:17], v[18:19], v[50:51] op_sel_hi:[1,0]
	v_pk_mul_f32 v[20:21], v[20:21], v[50:51] op_sel_hi:[1,0]
	v_mov_b32_e32 v23, v14
	v_mov_b32_e32 v14, v13
	v_mov_b32_e32 v22, v12
	v_pk_mul_f32 v[12:13], v[14:15], v[16:17]
	v_pk_mul_f32 v[20:21], v[22:23], v[20:21]
	s_nop 7
	s_nop 1
	v_cvt_pk_bf16_f32 v13, v21, v13
	v_cvt_pk_bf16_f32 v12, v20, v12
	global_store_dwordx2 v[48:49], v[12:13], off offset:2560
	v_mov_b32_e32 v12, v140
	v_mov_b32_e32 v13, v141
	v_mov_b32_e32 v14, v142
	v_mov_b32_e32 v15, v143
	v_mov_b32_e32 v17, v10
	v_mov_b32_e32 v10, v9
	v_mov_b32_e32 v16, v8
	v_pk_mul_f32 v[8:9], v[10:11], v[50:51] op_sel_hi:[1,0]
	v_pk_mul_f32 v[16:17], v[16:17], v[50:51] op_sel_hi:[1,0]
	v_mov_b32_e32 v19, v14
	v_mov_b32_e32 v14, v13
	v_mov_b32_e32 v18, v12
	v_pk_mul_f32 v[8:9], v[8:9], v[14:15]
	v_pk_mul_f32 v[16:17], v[16:17], v[18:19]
	s_nop 7
	s_nop 1
	v_cvt_pk_bf16_f32 v9, v17, v9
	v_cvt_pk_bf16_f32 v8, v16, v8
	global_store_dwordx2 v[48:49], v[8:9], off offset:3072
	v_mov_b32_e32 v8, v144
	v_mov_b32_e32 v9, v145
	v_mov_b32_e32 v10, v146
	v_mov_b32_e32 v11, v147
	v_mov_b32_e32 v13, v6
	v_mov_b32_e32 v6, v5
	v_mov_b32_e32 v12, v4
	v_pk_mul_f32 v[4:5], v[6:7], v[50:51] op_sel_hi:[1,0]
	v_pk_mul_f32 v[12:13], v[12:13], v[50:51] op_sel_hi:[1,0]
	v_mov_b32_e32 v15, v10
	v_mov_b32_e32 v10, v9
	v_mov_b32_e32 v14, v8
	v_pk_mul_f32 v[4:5], v[4:5], v[10:11]
	v_pk_mul_f32 v[12:13], v[12:13], v[14:15]
	v_and_b32_sdwa v8, v5, v59 dst_sel:DWORD dst_unused:UNUSED_PAD src0_sel:WORD_1 src1_sel:DWORD
	v_and_b32_sdwa v9, v4, v59 dst_sel:DWORD dst_unused:UNUSED_PAD src0_sel:WORD_1 src1_sel:DWORD
	v_and_b32_sdwa v6, v13, v59 dst_sel:DWORD dst_unused:UNUSED_PAD src0_sel:WORD_1 src1_sel:DWORD
	v_and_b32_sdwa v7, v12, v59 dst_sel:DWORD dst_unused:UNUSED_PAD src0_sel:WORD_1 src1_sel:DWORD
	v_add3_u32 v5, v5, v8, s3
	v_add3_u32 v4, v4, v9, s3
	v_add3_u32 v7, v12, v7, s3
	v_add3_u32 v6, v13, v6, s3
	v_and_b32_e32 v5, 0xffff0000, v5
	v_and_b32_e32 v4, 0xffff0000, v4
	v_or_b32_sdwa v5, v5, v6 dst_sel:DWORD dst_unused:UNUSED_PAD src0_sel:DWORD src1_sel:WORD_1
	v_or_b32_sdwa v4, v4, v7 dst_sel:DWORD dst_unused:UNUSED_PAD src0_sel:DWORD src1_sel:WORD_1
	global_store_dwordx2 v[48:49], v[4:5], off offset:3584
	v_lshl_add_u64 v[48:49], v[48:49], 0, s[8:9]
	s_cbranch_scc1 .LBB0_1590

; __device__ __forceinline__ void rms_row_bf16(const Ctx& c, const float* xrow, const float* gain, bf16* orow, float* copy) {
;     const f32x4* xr = (const f32x4*)xrow + c.lane; f32x4 v[8]; float s = 0.f;
; #pragma unroll
;     for (int j = 0; j < 8; ++j) { v[j] = xr[64 * j]; s += (v[j].x * v[j].x + v[j].y * v[j].y) + (v[j].z * v[j].z + v[j].w * v[j].w); }
;     const float rs = rsqrtf(wave_sum(s) * (1.f / DM) + EPS);
; template <int L>
; __device__ __forceinline__ void layer_body(const Ctx& c, const Args& args, const XcdBarrier& bar, int lo, int hi) {
;     ...
;             for (int r = (c.gw + c.NGW - 1024) % c.NGW; r < 1024; r += c.NGW) rms_row_bf16(c, mem + (size_t)r * DM, norm_mem + L * DM, MEMN + (size_t)r * DM, nullptr);
.LBB0_3312:
	s_add_i32 s6, s11, 0xfffffc00
	s_sub_i32 s8, 0x400, s11
	s_ashr_i32 s7, s6, 31
	s_max_i32 s6, s6, s8
	s_mul_hi_u32 s8, s6, s12
	s_mul_i32 s8, s8, s10
	s_sub_i32 s6, s6, s8
	s_sub_i32 s8, s6, s10
	s_cmp_ge_u32 s6, s10
	s_cselect_b32 s6, s8, s6
	s_sub_i32 s8, s6, s10
	s_cmp_ge_u32 s6, s10
	s_cselect_b32 s6, s8, s6
	s_xor_b32 s6, s6, s7
	s_sub_i32 s6, s6, s7
	s_cmpk_gt_i32 s6, 0x3ff
	s_cbranch_scc1 .LBB0_3315
	v_mbcnt_lo_u32_b32 v3, -1, 0
	v_mbcnt_hi_u32_b32 v4, -1, v3
	v_and_b32_e32 v3, 64, v4
	v_add_u32_e32 v5, 64, v3
	v_xor_b32_e32 v3, 1, v4
	v_cmp_lt_i32_e32 vcc, v3, v5
	v_xor_b32_e32 v6, 2, v4
	v_readlane_b32 s8, v253, 15
	v_cndmask_b32_e32 v3, v4, v3, vcc
	v_cmp_lt_i32_e32 vcc, v6, v5
	v_readlane_b32 s9, v253, 16
	v_readlane_b32 s16, v253, 23
	v_cndmask_b32_e32 v6, v4, v6, vcc
	v_lshlrev_b32_e32 v51, 2, v6
	v_xor_b32_e32 v6, 4, v4
	v_cmp_lt_i32_e32 vcc, v6, v5
	v_readlane_b32 s17, v253, 24
	s_mov_b64 s[8:9], 0x4000
	v_cndmask_b32_e32 v6, v4, v6, vcc
	v_lshlrev_b32_e32 v54, 2, v6
	v_xor_b32_e32 v6, 8, v4
	v_cmp_lt_i32_e32 vcc, v6, v5
	s_ashr_i32 s7, s6, 31
	v_readlane_b32 s10, v253, 17
	v_cndmask_b32_e32 v6, v4, v6, vcc
	v_lshlrev_b32_e32 v55, 2, v6
	v_xor_b32_e32 v6, 16, v4
	v_cmp_lt_i32_e32 vcc, v6, v5
	v_readlane_b32 s11, v253, 18
	v_readlane_b32 s12, v253, 19
	v_cndmask_b32_e32 v6, v4, v6, vcc
	v_lshlrev_b32_e32 v56, 2, v6
	v_xor_b32_e32 v6, 32, v4
	v_cmp_lt_i32_e32 vcc, v6, v5
	v_mov_b32_e32 v5, 0
	v_readlane_b32 s13, v253, 20
	v_cndmask_b32_e32 v4, v4, v6, vcc
	v_lshlrev_b32_e32 v57, 2, v4
	v_lshlrev_b32_e32 v4, 4, v164
	v_lshl_add_u64 v[6:7], s[16:17], 0, v[4:5]
	v_lshl_add_u64 v[36:37], v[6:7], 0, s[8:9]
	s_mov_b64 s[8:9], 0x5000
	v_lshl_add_u64 v[38:39], v[6:7], 0, s[8:9]
	s_mov_b64 s[8:9], 0x5400
	v_lshl_add_u64 v[40:41], v[6:7], 0, s[8:9]
	s_mov_b64 s[8:9], 0x5800
	v_lshl_add_u64 v[42:43], v[6:7], 0, s[8:9]
	s_mov_b64 s[8:9], 0x5c00
	v_lshl_add_u64 v[44:45], v[6:7], 0, s[8:9]
	s_lshl_b64 s[8:9], s[6:7], 13
	s_add_u32 s8, s10, s8
	s_addc_u32 s9, s11, s9
	v_lshl_add_u64 v[6:7], s[8:9], 0, v[4:5]
	s_mov_b64 s[8:9], 0x1000
	s_ashr_i32 s87, s86, 31
	s_waitcnt lgkmcnt(0)
	v_lshl_add_u64 v[46:47], v[6:7], 0, s[8:9]
	s_lshl_b64 s[8:9], s[86:87], 13
	s_lshl_b64 s[10:11], s[6:7], 12
	v_readlane_b32 s12, v253, 0
	v_readlane_b32 s13, v253, 1
	s_add_u32 s10, s12, s10
	v_lshlrev_b32_e32 v4, 3, v164
	s_addc_u32 s11, s13, s11
	v_lshl_add_u64 v[4:5], s[10:11], 0, v[4:5]
	s_mov_b64 s[10:11], 0x31600000
	v_lshlrev_b32_e32 v3, 2, v3
	v_lshl_add_u64 v[48:49], v[4:5], 0, s[10:11]
	s_lshl_b64 s[10:11], s[86:87], 12
	v_mov_b32_e32 v58, 0x358637bd
	s_movk_i32 s7, 0x7fff
	v_mov_b32_e32 v59, 1
	s_mov_b32 s12, 0x800000
	v_readlane_b32 s14, v253, 21
	v_readlane_b32 s15, v253, 22
	v_readlane_b32 s18, v253, 25
	v_readlane_b32 s19, v253, 26
	v_readlane_b32 s20, v253, 27
	v_readlane_b32 s21, v253, 28
	v_readlane_b32 s22, v253, 29
	v_readlane_b32 s23, v253, 30
	global_load_dwordx4 v[68:71], v[36:37], off
	global_load_dwordx4 v[80:83], v[36:37], off offset:1024
	global_load_dwordx4 v[84:87], v[36:37], off offset:2048
	global_load_dwordx4 v[88:91], v[36:37], off offset:3072
	global_load_dwordx4 v[120:123], v[38:39], off
	global_load_dwordx4 v[124:127], v[40:41], off
	global_load_dwordx4 v[128:131], v[42:43], off
	global_load_dwordx4 v[132:135], v[44:45], off
	s_waitcnt vmcnt(0)
.LBB0_3314:
	global_load_dwordx4 v[32:35], v[46:47], off offset:-4096
	global_load_dwordx4 v[28:31], v[46:47], off offset:-3072
	global_load_dwordx4 v[24:27], v[46:47], off offset:-2048
	global_load_dwordx4 v[20:23], v[46:47], off offset:-1024
	global_load_dwordx4 v[12:15], v[46:47], off
	global_load_dwordx4 v[16:19], v[46:47], off offset:1024
	s_add_i32 s6, s6, s86
	s_cmpk_lt_i32 s6, 0x400
	s_waitcnt vmcnt(0)
	v_mov_b32_e32 v6, v33
	v_mov_b32_e32 v7, v29
	v_mov_b32_e32 v4, v32
	v_mov_b32_e32 v5, v28
	v_pk_mul_f32 v[6:7], v[6:7], v[6:7]
	v_mov_b32_e32 v8, v35
	v_mov_b32_e32 v9, v31
	v_pk_fma_f32 v[4:5], v[4:5], v[4:5], v[6:7]
	v_mov_b32_e32 v6, v34
	v_mov_b32_e32 v7, v30
	v_pk_mul_f32 v[8:9], v[8:9], v[8:9]
	s_nop 0
	v_pk_fma_f32 v[6:7], v[6:7], v[6:7], v[8:9]
	v_pk_mul_f32 v[8:9], v[24:25], v[24:25]
	v_pk_add_f32 v[4:5], v[4:5], v[6:7]
	v_pk_mul_f32 v[6:7], v[26:27], v[26:27]
	v_pk_add_f32 v[4:5], v[4:5], v[4:5] op_sel:[0,1] op_sel_hi:[1,0]
	v_pk_mov_b32 v[10:11], v[8:9], v[6:7] op_sel:[1,0]
	v_mov_b32_e32 v9, v7
	v_pk_add_f32 v[6:7], v[10:11], v[8:9]
	v_mul_f32_e32 v8, v12, v12
	v_mul_f32_e32 v9, v13, v13
	v_pk_add_f32 v[6:7], v[6:7], v[6:7] op_sel:[0,1] op_sel_hi:[1,0]
	v_mov_b32_e32 v5, v8
	v_mov_b32_e32 v7, v9
	v_pk_add_f32 v[4:5], v[4:5], v[6:7]
	v_mul_f32_e32 v6, v21, v21
	v_mul_f32_e32 v8, v23, v23
	v_mul_f32_e32 v10, v14, v14
	v_mul_f32_e32 v11, v15, v15
	v_pk_fma_f32 v[6:7], v[20:21], v[20:21], v[6:7] op_sel_hi:[1,1,0]
	v_pk_fma_f32 v[8:9], v[22:23], v[22:23], v[8:9] op_sel_hi:[1,1,0]
	v_mov_b32_e32 v7, v10
	v_mov_b32_e32 v9, v11
	v_pk_add_f32 v[6:7], v[6:7], v[8:9]
	s_nop 0
	v_pk_add_f32 v[52:53], v[4:5], v[6:7]
	v_pk_mul_f32 v[4:5], v[18:19], v[18:19]
	v_pk_mul_f32 v[6:7], v[16:17], v[16:17]
	v_pk_add_f32 v[52:53], v[52:53], v[52:53] op_sel:[0,1] op_sel_hi:[1,0]
	v_pk_mov_b32 v[8:9], v[6:7], v[4:5] op_sel:[1,0]
	v_mov_b32_e32 v7, v5
	v_pk_add_f32 v[60:61], v[8:9], v[6:7]
	global_load_dwordx4 v[8:11], v[46:47], off offset:2048
	global_load_dwordx4 v[4:7], v[46:47], off offset:3072
	v_pk_add_f32 v[60:61], v[60:61], v[60:61] op_sel:[0,1] op_sel_hi:[1,0]
	v_lshl_add_u64 v[46:47], v[46:47], 0, s[8:9]
	s_waitcnt vmcnt(0)
; __device__ __forceinline__ void rms_row_bf16(const Ctx& c, const float* xrow, const float* gain, bf16* orow, float* copy) {
;     ...
;     for (int j = 0; j < 8; ++j) { v[j] = xr[64 * j]; s += (v[j].x * v[j].x + v[j].y * v[j].y) + (v[j].z * v[j].z + v[j].w * v[j].w); }
;     const float rs = rsqrtf(wave_sum(s) * (1.f / DM) + EPS);
	v_mul_f32_e32 v50, v4, v4
	v_mul_f32_e32 v62, v5, v5
	v_mov_b32_e32 v53, v50
	v_mov_b32_e32 v61, v62
	v_mul_f32_e32 v50, v9, v9
	v_mul_f32_e32 v63, v6, v6
	v_pk_add_f32 v[52:53], v[52:53], v[60:61]
	v_pk_fma_f32 v[60:61], v[8:9], v[8:9], v[50:51] op_sel_hi:[1,1,0]
	v_mul_f32_e32 v50, v11, v11
	v_mul_f32_e32 v64, v7, v7
	v_mov_b32_e32 v61, v63
	v_pk_fma_f32 v[62:63], v[10:11], v[10:11], v[50:51] op_sel_hi:[1,1,0]
	s_nop 0
	v_mov_b32_e32 v63, v64
	v_pk_add_f32 v[60:61], v[60:61], v[62:63]
	s_nop 0
	v_pk_add_f32 v[52:53], v[52:53], v[60:61]
	v_mov_b32_e32 v60, v68
	v_mov_b32_e32 v61, v69
	v_mov_b32_e32 v62, v70
	v_mov_b32_e32 v63, v71
	v_add_f32_e32 v50, v52, v53
	v_mov_b32_e32 v53, v34
	v_mov_b32_e32 v34, v33
	s_waitcnt lgkmcnt(0)
	s_nop 1
	v_add_f32_dpp v50, v50, v50 quad_perm:[1,0,3,2] row_mask:0xf bank_mask:0xf
	s_waitcnt lgkmcnt(0)
	s_nop 1
	v_add_f32_dpp v50, v50, v50 quad_perm:[2,3,0,1] row_mask:0xf bank_mask:0xf
	s_waitcnt lgkmcnt(0)
	s_nop 1
	v_add_f32_dpp v50, v50, v50 row_half_mirror row_mask:0xf bank_mask:0xf
	s_waitcnt lgkmcnt(0)
	s_nop 1
	v_add_f32_dpp v50, v50, v50 row_mirror row_mask:0xf bank_mask:0xf
	s_waitcnt lgkmcnt(0)
	v_mov_b32_e32 v52, v50
	s_nop 1
	v_permlane16_swap_b32_e32 v50, v52
	v_add_f32_e32 v50, v50, v52
	s_waitcnt lgkmcnt(0)
; __device__ __forceinline__ unsigned pk2(float lo, float hi) { return f2bf(lo) | (f2bf(hi) << 16); }
; __device__ __forceinline__ void rms_row_bf16(const Ctx& c, const float* xrow, const float* gain, bf16* orow, float* copy) {
;     ...
;     const float rs = rsqrtf(wave_sum(s) * (1.f / DM) + EPS);
;     if (copy) {
; #pragma unroll
;         for (int j = 0; j < 8; ++j) ((f32x4*)copy + c.lane)[64 * j] = v[j]; }
;     const f32x4* gr = (const f32x4*)gain + c.lane; v2u* o8 = (v2u*)orow + c.lane;
; #pragma unroll
;     for (int j = 0; j < 8; ++j) { const f32x4 g = gr[64 * j]; v2u o; o.x = pk2(v[j].x * rs * g.x, v[j].y * rs * g.y); o.y = pk2(v[j].z * rs * g.z, v[j].w * rs * g.w); o8[64 * j] = o; }
	v_mov_b32_e32 v52, v50
	s_nop 1
	v_permlane32_swap_b32_e32 v50, v52
	v_add_f32_e32 v50, v50, v52
	v_fmamk_f32 v50, v50, 0x3a000000, v58
	v_cmp_gt_f32_e32 vcc, s12, v50
	v_mul_f32_e32 v52, 0x4b800000, v50
	v_mov_b32_e32 v64, v60
	v_cndmask_b32_e32 v50, v50, v52, vcc
	v_rsq_f32_e32 v50, v50
	v_mov_b32_e32 v65, v62
	v_mov_b32_e32 v62, v61
	v_mul_f32_e32 v52, 0x45800000, v50
	v_cndmask_b32_e32 v50, v50, v52, vcc
	v_mov_b32_e32 v52, v32
	v_pk_mul_f32 v[52:53], v[52:53], v[50:51] op_sel_hi:[1,0]
	v_pk_mul_f32 v[32:33], v[34:35], v[50:51] op_sel_hi:[1,0]
	v_pk_mul_f32 v[52:53], v[64:65], v[52:53]
	v_pk_mul_f32 v[32:33], v[62:63], v[32:33]
	v_and_b32_sdwa v34, v53, v59 dst_sel:DWORD dst_unused:UNUSED_PAD src0_sel:WORD_1 src1_sel:DWORD
	v_and_b32_sdwa v35, v52, v59 dst_sel:DWORD dst_unused:UNUSED_PAD src0_sel:WORD_1 src1_sel:DWORD
	v_add3_u32 v35, v52, v35, s7
	v_add3_u32 v34, v53, v34, s7
	v_and_b32_sdwa v52, v33, v59 dst_sel:DWORD dst_unused:UNUSED_PAD src0_sel:WORD_1 src1_sel:DWORD
	v_and_b32_sdwa v53, v32, v59 dst_sel:DWORD dst_unused:UNUSED_PAD src0_sel:WORD_1 src1_sel:DWORD
	v_add3_u32 v33, v33, v52, s7
	v_add3_u32 v32, v32, v53, s7
	v_and_b32_e32 v33, 0xffff0000, v33
	v_and_b32_e32 v32, 0xffff0000, v32
	v_or_b32_sdwa v33, v33, v34 dst_sel:DWORD dst_unused:UNUSED_PAD src0_sel:DWORD src1_sel:WORD_1
	v_or_b32_sdwa v32, v32, v35 dst_sel:DWORD dst_unused:UNUSED_PAD src0_sel:DWORD src1_sel:WORD_1
	global_store_dwordx2 v[48:49], v[32:33], off
	v_mov_b32_e32 v32, v80
	v_mov_b32_e32 v33, v81
	v_mov_b32_e32 v34, v82
	v_mov_b32_e32 v35, v83
	v_mov_b32_e32 v53, v30
	v_mov_b32_e32 v30, v29
	v_mov_b32_e32 v52, v28
	v_pk_mul_f32 v[28:29], v[30:31], v[50:51] op_sel_hi:[1,0]
	v_pk_mul_f32 v[52:53], v[52:53], v[50:51] op_sel_hi:[1,0]
	v_mov_b32_e32 v61, v34
	v_mov_b32_e32 v34, v33
	v_mov_b32_e32 v60, v32
	v_pk_mul_f32 v[28:29], v[34:35], v[28:29]
	v_pk_mul_f32 v[52:53], v[60:61], v[52:53]
	s_nop 7
	s_nop 1
	v_cvt_pk_bf16_f32 v29, v53, v29
	v_cvt_pk_bf16_f32 v28, v52, v28
	global_store_dwordx2 v[48:49], v[28:29], off offset:512
	v_mov_b32_e32 v28, v84
	v_mov_b32_e32 v29, v85
	v_mov_b32_e32 v30, v86
	v_mov_b32_e32 v31, v87
	v_mov_b32_e32 v33, v26
	v_mov_b32_e32 v26, v25
	v_mov_b32_e32 v32, v24
	v_pk_mul_f32 v[24:25], v[26:27], v[50:51] op_sel_hi:[1,0]
	v_pk_mul_f32 v[32:33], v[32:33], v[50:51] op_sel_hi:[1,0]
	v_mov_b32_e32 v35, v30
	v_mov_b32_e32 v30, v29
	v_mov_b32_e32 v34, v28
	v_pk_mul_f32 v[24:25], v[30:31], v[24:25]
	v_pk_mul_f32 v[32:33], v[34:35], v[32:33]
	s_nop 7
	s_nop 1
	v_cvt_pk_bf16_f32 v25, v33, v25
	v_cvt_pk_bf16_f32 v24, v32, v24
	global_store_dwordx2 v[48:49], v[24:25], off offset:1024
	v_mov_b32_e32 v24, v88
	v_mov_b32_e32 v25, v89
	v_mov_b32_e32 v26, v90
	v_mov_b32_e32 v27, v91
	v_mov_b32_e32 v29, v22
	v_mov_b32_e32 v22, v21
	v_mov_b32_e32 v28, v20
	v_pk_mul_f32 v[20:21], v[22:23], v[50:51] op_sel_hi:[1,0]
	v_pk_mul_f32 v[28:29], v[28:29], v[50:51] op_sel_hi:[1,0]
	v_mov_b32_e32 v31, v26
	v_mov_b32_e32 v26, v25
	v_mov_b32_e32 v30, v24
	v_pk_mul_f32 v[20:21], v[26:27], v[20:21]
	v_pk_mul_f32 v[28:29], v[30:31], v[28:29]
	s_nop 7
	s_nop 1
	v_cvt_pk_bf16_f32 v21, v29, v21
	v_cvt_pk_bf16_f32 v20, v28, v20
	global_store_dwordx2 v[48:49], v[20:21], off offset:1536
	v_mov_b32_e32 v20, v120
	v_mov_b32_e32 v21, v121
	v_mov_b32_e32 v22, v122
	v_mov_b32_e32 v23, v123
	v_mov_b32_e32 v25, v14
	v_mov_b32_e32 v14, v13
	v_mov_b32_e32 v24, v12
	v_pk_mul_f32 v[12:13], v[14:15], v[50:51] op_sel_hi:[1,0]
	v_pk_mul_f32 v[24:25], v[24:25], v[50:51] op_sel_hi:[1,0]
	v_mov_b32_e32 v27, v22
	v_mov_b32_e32 v22, v21
	v_mov_b32_e32 v26, v20
	v_pk_mul_f32 v[12:13], v[22:23], v[12:13]
	v_pk_mul_f32 v[24:25], v[26:27], v[24:25]
	s_nop 7
	s_nop 1
	v_cvt_pk_bf16_f32 v13, v25, v13
	v_cvt_pk_bf16_f32 v12, v24, v12
	global_store_dwordx2 v[48:49], v[12:13], off offset:2048
	v_mov_b32_e32 v12, v124
	v_mov_b32_e32 v13, v125
	v_mov_b32_e32 v14, v126
	v_mov_b32_e32 v15, v127
	v_mov_b32_e32 v21, v18
	v_mov_b32_e32 v18, v17
	v_mov_b32_e32 v20, v16
	v_pk_mul_f32 v[16:17], v[18:19], v[50:51] op_sel_hi:[1,0]
	v_pk_mul_f32 v[20:21], v[20:21], v[50:51] op_sel_hi:[1,0]
	v_mov_b32_e32 v23, v14
	v_mov_b32_e32 v14, v13
	v_mov_b32_e32 v22, v12
	v_pk_mul_f32 v[12:13], v[14:15], v[16:17]
	v_pk_mul_f32 v[20:21], v[22:23], v[20:21]
	s_nop 7
	s_nop 1
	v_cvt_pk_bf16_f32 v13, v21, v13
	v_cvt_pk_bf16_f32 v12, v20, v12
	global_store_dwordx2 v[48:49], v[12:13], off offset:2560
	v_mov_b32_e32 v12, v128
	v_mov_b32_e32 v13, v129
	v_mov_b32_e32 v14, v130
	v_mov_b32_e32 v15, v131
	v_mov_b32_e32 v17, v10
	v_mov_b32_e32 v10, v9
	v_mov_b32_e32 v16, v8
	v_pk_mul_f32 v[8:9], v[10:11], v[50:51] op_sel_hi:[1,0]
	v_pk_mul_f32 v[16:17], v[16:17], v[50:51] op_sel_hi:[1,0]
	v_mov_b32_e32 v19, v14
	v_mov_b32_e32 v14, v13
	v_mov_b32_e32 v18, v12
	v_pk_mul_f32 v[8:9], v[8:9], v[14:15]
	v_pk_mul_f32 v[16:17], v[16:17], v[18:19]
	s_nop 7
	s_nop 1
	v_cvt_pk_bf16_f32 v9, v17, v9
	v_cvt_pk_bf16_f32 v8, v16, v8
	global_store_dwordx2 v[48:49], v[8:9], off offset:3072
	v_mov_b32_e32 v8, v132
	v_mov_b32_e32 v9, v133
	v_mov_b32_e32 v10, v134
	v_mov_b32_e32 v11, v135
	v_mov_b32_e32 v13, v6
	v_mov_b32_e32 v6, v5
	v_mov_b32_e32 v12, v4
	v_pk_mul_f32 v[4:5], v[6:7], v[50:51] op_sel_hi:[1,0]
	v_pk_mul_f32 v[12:13], v[12:13], v[50:51] op_sel_hi:[1,0]
	v_mov_b32_e32 v15, v10
	v_mov_b32_e32 v10, v9
	v_mov_b32_e32 v14, v8
	v_pk_mul_f32 v[4:5], v[4:5], v[10:11]
	v_pk_mul_f32 v[12:13], v[12:13], v[14:15]
	v_and_b32_sdwa v8, v5, v59 dst_sel:DWORD dst_unused:UNUSED_PAD src0_sel:WORD_1 src1_sel:DWORD
	v_and_b32_sdwa v9, v4, v59 dst_sel:DWORD dst_unused:UNUSED_PAD src0_sel:WORD_1 src1_sel:DWORD
	v_and_b32_sdwa v6, v13, v59 dst_sel:DWORD dst_unused:UNUSED_PAD src0_sel:WORD_1 src1_sel:DWORD
	v_and_b32_sdwa v7, v12, v59 dst_sel:DWORD dst_unused:UNUSED_PAD src0_sel:WORD_1 src1_sel:DWORD
	v_add3_u32 v5, v5, v8, s7
	v_add3_u32 v4, v4, v9, s7
	v_add3_u32 v7, v12, v7, s7
	v_add3_u32 v6, v13, v6, s7
	v_and_b32_e32 v5, 0xffff0000, v5
	v_and_b32_e32 v4, 0xffff0000, v4
	v_or_b32_sdwa v5, v5, v6 dst_sel:DWORD dst_unused:UNUSED_PAD src0_sel:DWORD src1_sel:WORD_1
	v_or_b32_sdwa v4, v4, v7 dst_sel:DWORD dst_unused:UNUSED_PAD src0_sel:DWORD src1_sel:WORD_1
	global_store_dwordx2 v[48:49], v[4:5], off offset:3584
	v_lshl_add_u64 v[48:49], v[48:49], 0, s[10:11]
	s_cbranch_scc1 .LBB0_3314
